# E20 + one static s_setprio 1 for waves 4-7 during the attention phase (reset to 0 at phase exit)
# speedup vs baseline: 1.0046x; 1.0046x over previous
; #define LAS __attribute__((address_space(3)))
;     __device__ __forceinline__ unsigned char* ws() const { return (unsigned char*)raw(25); }
; template <int TYPE> __device__ __forceinline__ void attn_unit(LAS unsigned char* lds, const AttnUnit& U) {
;     constexpr int ND = TYPE == 0 ? 6 : 4;
;     constexpr float SC = (TYPE == 0 ? 0.10206207261596575f : 0.125f) * LOG2E;
;     constexpr float THR = 40.0f;
;     int tid_ = threadIdx.x; asm volatile("" : "+v"(tid_));
;     const int tid = tid_, lane = tid & 63, wid = __builtin_amdgcn_readfirstlane(tid >> 6), r32 = lane & 31, hi = lane >> 5;
;     const int NT = (U.qpos0 + (U.nq > 32 ? 256 : 32) - 1) / 64 + 1;
;     const bool active = wid * 32 < U.nq;
;     const int NTw = active ? (U.qpos0 + 32 * wid + 31) / 64 + 1 : 0;
;     LAS float* wsf = (LAS float*)(lds + 82944) + wid * 64;
;     ...
;     const unsigned lds0 = (unsigned)(uintptr_t)lds;
;     const int lastrow = U.nkeys - 1 - 64 * (NT - 1);
;     const int lr8 = 8 * wid + (lane >> 3);
;     const int kch = (lane & 7) ^ ((4 * wid + (lane >> 4)) & 7);
;     const int vch = (lane & 7) ^ (((lane >> 4) & 1) * 4);
;     const int rr16 = 16 * (wid & 3) + (lane >> 2), rch = (lane & 3) ^ ((lane >> 4) & 3);
;     const unsigned voK = (unsigned)(lr8 * U.kpitch * 2 + 16 * kch), voKl = (unsigned)(min(lr8, lastrow) * U.kpitch * 2 + 16 * kch);
;     const unsigned voV = (unsigned)(lr8 * U.vpitch * 2 + 16 * vch), voVl = (unsigned)(min(lr8, lastrow) * U.vpitch * 2 + 16 * vch);
;     const unsigned voA = TYPE == 0 ? (unsigned)(rr16 * 64 + 16 * rch) : (unsigned)(lane * 32), voAl = TYPE == 0 ? (unsigned)(min(rr16, lastrow) * 64 + 16 * rch) : (unsigned)(min(lane, lastrow) * 32);
; __device__ __forceinline__ void attn_phase(const Ctx& a, LAS unsigned char* lds) {
;     unsigned char* ws = a.ws();
;     const bf16* PROJ = (const bf16*)(ws + WS_PROJ); const bf16* QM = (const bf16*)(ws + WS_QM); const bf16* KV = (const bf16*)(ws + WS_KV); const bf16* KROPE = (const bf16*)(ws + WS_KROPE);
;     const bf16* FKS = (const bf16*)(ws + WS_FKS); const bf16* FVS = (const bf16*)(ws + WS_FVS); const float* LKB = (const float*)(ws + WS_LK); bf16* OB = (bf16*)(ws + WS_XN);
;     unsigned* qctr = (unsigned*)(ws + WS_QCTR);
;     const int myx = (int)(__builtin_amdgcn_s_getreg((3 << 11) | 20) & 7u);
;     LAS int* slot = (LAS int*)(lds + PTR_OFF + 256);
;     int qoff = 0;
.LBB0_635:
	v_writelane_b32 v227, s92, 7
	s_nop 1
	v_writelane_b32 v227, s93, 8
	v_writelane_b32 v227, s91, 9
	v_writelane_b32 v227, s90, 10
	v_writelane_b32 v227, s89, 11
	v_writelane_b32 v227, s88, 12
	v_writelane_b32 v227, s87, 13
	v_writelane_b32 v227, s83, 14
	v_writelane_b32 v227, s86, 15
	s_nop 1
	v_writelane_b32 v227, s87, 16
	v_writelane_b32 v227, s84, 17
	s_nop 1
	v_writelane_b32 v227, s85, 18
	v_writelane_b32 v227, s82, 19
	v_writelane_b32 v227, s81, 20
	s_or_b64 exec, exec, s[0:1]
	s_add_i32 s0, 0, 0x200c8
	v_mov_b32_e32 v0, s0
	s_waitcnt lgkmcnt(0)
	s_barrier
	ds_read_b64 v[0:1], v0
	s_mov_b32 s97, 0
	s_getreg_b32 s16, hwreg(HW_REG_XCC_ID, 0, 4)
	v_mov_b32_e32 v185, 1
	v_and_b32_e32 v254, 63, v184
	v_bfe_u32 v252, v254, 4, 1
	v_and_b32_e32 v253, 15, v254
	v_mov_b32_e32 v248, 0x3f803f80
	v_cmp_eq_u32_e32 vcc, v253, v252
	s_nop 1
	v_cndmask_b32_e32 v248, 0, v248, vcc
	v_and_b32_e32 v252, 1, v254
	v_lshlrev_b32_e32 v252, 6, v252
	v_and_b32_e32 v255, 48, v254
	v_add_u32_e32 v252, v252, v255
	v_lshrrev_b32_e32 v255, 5, v254
	v_lshlrev_b32_e32 v255, 4, v255
	v_sub_u32_e32 v252, v252, v255
	v_and_b32_e32 v254, 0x1c0, v184
	v_lshlrev_b32_e32 v254, 2, v254
	v_add_u32_e32 v254, v254, v255
	v_add_u32_e32 v254, 0x14400, v254
	v_mov_b32_e32 v249, v248
	v_mov_b32_e32 v250, v248
	v_mov_b32_e32 v251, v248
	v_readfirstlane_b32 s0, v184
	s_cmp_lt_u32 s0, 0x100
	s_cbranch_scc1 .Lattn_prio_skip
	s_setprio 1
.Lattn_prio_skip:
	s_mov_b32 s90, 0x42200000
	s_waitcnt lgkmcnt(0)
	v_readfirstlane_b32 s1, v0
	v_readfirstlane_b32 s0, v1
	s_add_u32 s2, s1, 0x13497000
	v_writelane_b32 v227, s2, 21
	s_addc_u32 s2, s0, 0
	v_writelane_b32 v227, s2, 22
	s_add_u32 s2, s1, 0x295f7000
	v_writelane_b32 v227, s2, 23
	s_addc_u32 s2, s0, 0
	v_writelane_b32 v227, s2, 24
	s_add_u32 s2, s1, 0x2f657000
	v_writelane_b32 v227, s2, 25
	s_addc_u32 s2, s0, 0
	v_writelane_b32 v227, s2, 26
	s_add_u32 s2, s1, 0x2d93000
	v_writelane_b32 v227, s2, 27
	s_addc_u32 s2, s0, 0
	v_writelane_b32 v227, s2, 28
	s_add_u32 s2, s1, 0xe437000
	v_writelane_b32 v227, s2, 29
	s_addc_u32 s2, s0, 0
	v_writelane_b32 v227, s2, 30
	s_add_u32 s2, s1, 0x10467000
	v_writelane_b32 v227, s2, 31
	s_addc_u32 s2, s0, 0
	v_writelane_b32 v227, s2, 32
	s_add_u32 s2, s1, 0x2990000
	v_writelane_b32 v227, s2, 33
	s_addc_u32 s2, s0, 0
	v_writelane_b32 v227, s2, 34
	s_add_u32 s2, s1, 0x3397000
	v_writelane_b32 v227, s2, 35
	s_addc_u32 s2, s0, 0
	v_writelane_b32 v227, s2, 36
	s_add_u32 s2, s1, 0x3b6d7000
	s_addc_u32 s3, s0, 0
	v_writelane_b32 v227, s2, 37
	v_mov_b32_e32 v1, 0
	s_mov_b32 s76, 0x3f803f80
	v_writelane_b32 v227, s3, 38
	s_add_u32 s2, s1, 0x2890000
	s_addc_u32 s3, s0, 0
	v_writelane_b32 v227, s2, 39
	s_add_i32 s0, 0, 0x20100
	v_mov_b32_e32 v186, s0
	v_writelane_b32 v227, s3, 40
	v_writelane_b32 v227, s0, 41
	s_add_i32 s0, 0, 0x14100
	v_writelane_b32 v227, s0, 42
	s_add_i32 s0, 0, 0x14200
	v_writelane_b32 v227, s0, 43
	s_add_i32 s0, 0, 0x14300
	v_writelane_b32 v227, s0, 44
	s_add_i32 s0, 0, 0x1000
	v_writelane_b32 v227, s0, 45
	s_add_i32 s0, 0, 0x800
	s_add_i32 s93, 0, 0x14000
	v_writelane_b32 v227, s0, 46
	s_movk_i32 s37, 0x7fff
	v_mov_b32_e32 v187, 0x100
	v_mov_b32_e32 v188, 0xff800000
	v_mov_b32_e32 v189, 0x2000
	v_mov_b32_e32 v190, 0
	v_writelane_b32 v227, s93, 47
	v_writelane_b32 v227, s16, 48
	s_branch .LBB0_637

; __device__ __forceinline__ unsigned xb_ld(unsigned* p)              { return __hip_atomic_load(p, __ATOMIC_RELAXED, __HIP_MEMORY_SCOPE_AGENT); }
; __device__ __forceinline__ void xcd_barrier_complete(unsigned* bar, unsigned x, unsigned& nloc, unsigned& nx) {
;     const unsigned G = gridDim.x * gridDim.y * gridDim.z;
;     unsigned sum, cnt, mine, sp = 0u;
;     for (;;) {
;         sum = 0u; cnt = 0u; mine = 0u;
; #pragma unroll
;         for (unsigned j = 0; j < 16; ++j) { const unsigned c = xb_ld(&bar[XB_XCNT(j)]); sum += c; cnt += (c > 0u) ? 1u : 0u; mine = (j == x) ? c : mine; }
; __device__ __forceinline__ void xcd_barrier(const XcdBarrier& b) {
;     asm volatile("s_waitcnt vmcnt(0)" ::: "memory");
;     __syncthreads();
;     if (threadIdx.x == 0) {
;         unsigned* bar = b.bar;
;         __builtin_amdgcn_s_waitcnt(0);
;         unsigned nloc = b.st[0], nx = b.st[1];
;         if (nloc == 0u) { xcd_barrier_complete(bar, b.x, nloc, nx); b.st[0] = nloc; b.st[1] = nx; }
.LBB0_806:
	s_setprio 0
	s_cbranch_execz .LBB0_637
	s_waitcnt vmcnt(0)
	s_barrier
	s_mov_b64 s[0:1], exec
	v_readlane_b32 s2, v227, 0
	v_readlane_b32 s70, v227, 15
	v_readlane_b32 s3, v227, 1
	v_readlane_b32 s68, v227, 17
	v_readlane_b32 s71, v227, 16
	v_readlane_b32 s76, v227, 7
	s_and_b64 s[2:3], s[0:1], s[2:3]
	v_readlane_b32 s65, v227, 20
	v_readlane_b32 s66, v227, 19
	v_readlane_b32 s69, v227, 18
	v_readlane_b32 s67, v227, 14
	v_readlane_b32 s71, v227, 13
	v_readlane_b32 s72, v227, 12
	v_readlane_b32 s73, v227, 11
	v_readlane_b32 s74, v227, 10
	v_readlane_b32 s75, v227, 9
	v_readlane_b32 s77, v227, 8
	s_mov_b64 exec, s[2:3]
	s_cbranch_execz .LBB0_851
	s_add_i32 s2, 0, 0x20200
	v_mov_b32_e32 v0, s2
	s_waitcnt vmcnt(0) expcnt(0) lgkmcnt(0)
	ds_read_b32 v2, v0
	s_add_i32 s2, 0, 0x20204
	v_mov_b32_e32 v0, s2
	ds_read_b32 v0, v0
	s_waitcnt lgkmcnt(1)
	v_cmp_ne_u32_e32 vcc, 0, v2
	s_cbranch_vccnz .LBB0_822
	s_add_u32 s2, s72, 0x3b6d8200
	s_addc_u32 s3, s71, 0
	s_add_u32 s6, s72, 0x3b6d8400
	s_addc_u32 s7, s71, 0
	s_add_u32 s8, s72, 0x3b6d8500
	s_addc_u32 s9, s71, 0
	s_add_u32 s10, s72, 0x3b6d8600
	s_addc_u32 s11, s71, 0
	s_add_u32 s12, s72, 0x3b6d8700
	s_addc_u32 s13, s71, 0
	s_add_u32 s14, s72, 0x3b6d8800
	s_addc_u32 s15, s71, 0
	s_add_u32 s16, s72, 0x3b6d8900
	s_addc_u32 s17, s71, 0
	s_add_u32 s18, s72, 0x3b6d8a00
	s_addc_u32 s19, s71, 0
	s_add_u32 s20, s72, 0x3b6d8b00
	s_addc_u32 s21, s71, 0
	s_add_u32 s24, s72, 0x3b6d8c00
	s_addc_u32 s25, s71, 0
	s_add_u32 s26, s72, 0x3b6d8d00
	s_addc_u32 s27, s71, 0
	s_add_u32 s28, s72, 0x3b6d8e00
	s_addc_u32 s29, s71, 0
	s_add_u32 s30, s72, 0x3b6d8f00
	s_addc_u32 s31, s71, 0
	s_add_u32 s34, s72, 0x3b6d9000
	s_addc_u32 s35, s71, 0
	s_add_u32 s36, s72, 0x3b6d9100
	s_addc_u32 s37, s71, 0
	s_add_u32 s38, s72, 0x3b6d9200
	s_addc_u32 s39, s71, 0
	s_add_u32 s40, s72, 0x3b6d9300
	s_mul_i32 s22, s69, s67
	s_addc_u32 s41, s71, 0
	s_mul_i32 s22, s22, s68
	s_mov_b32 s23, 1
	s_mov_b64 s[4:5], 0
	s_waitcnt lgkmcnt(0)
	v_mov_b64_e32 v[0:1], s[6:7]
	v_mov_b64_e32 v[2:3], s[8:9]
	v_mov_b64_e32 v[4:5], s[10:11]
	v_mov_b64_e32 v[6:7], s[12:13]
	v_mov_b64_e32 v[8:9], s[14:15]
	v_mov_b64_e32 v[10:11], s[16:17]
	v_mov_b64_e32 v[12:13], s[18:19]
	v_mov_b64_e32 v[14:15], s[20:21]
	v_mov_b64_e32 v[16:17], s[24:25]
	v_mov_b64_e32 v[18:19], s[26:27]
	v_mov_b64_e32 v[20:21], s[28:29]
	v_mov_b64_e32 v[22:23], s[30:31]
	v_mov_b64_e32 v[24:25], s[34:35]
	v_mov_b64_e32 v[26:27], s[36:37]
	v_mov_b64_e32 v[28:29], s[38:39]
	v_mov_b64_e32 v[30:31], s[40:41]
	s_branch .LBB0_812
